# NSA gate-load hoisting: gates 2 and 3 of the NSA unit loaded early into the free v234 instead of load+vmcnt(0) at the point of use
# speedup vs baseline: 1.0042x; 1.0042x over previous
.LBB0_1491:
	ds_bpermute_b32 v0, v205, v187
	v_mov_b32_e32 v189, v196
	s_waitcnt lgkmcnt(0)
	v_add_f32_e32 v0, v187, v0
	v_max_f32_e32 v0, 0xda24260, v0
	s_waitcnt vmcnt(0)
	v_div_scale_f32 v3, s[0:1], v0, v0, v234
	v_rcp_f32_e32 v4, v3
	v_readlane_b32 s0, v254, 43
	v_readlane_b32 s1, v254, 44
	v_fma_f32 v5, -v3, v4, 1.0
	v_fmac_f32_e32 v4, v5, v4
	v_div_scale_f32 v5, vcc, v234, v0, v234
	v_mul_f32_e32 v6, v5, v4
	v_fma_f32 v7, -v3, v6, v5
	v_fmac_f32_e32 v6, v7, v4
	v_fma_f32 v3, -v3, v6, v5
	v_div_fmas_f32 v3, v3, v4, v6
	v_div_fixup_f32 v0, v3, v0, v234
	ds_read2st64_b32 v[2:3], v206 offset0:4 offset1:5
	ds_read2st64_b32 v[6:7], v206 offset0:20 offset1:21
	s_waitcnt lgkmcnt(1)
	v_pk_fma_f32 v[4:5], v[34:35], v[0:1], v[2:3] op_sel_hi:[1,0,1]
	s_waitcnt lgkmcnt(0)
	v_pk_fma_f32 v[2:3], v[50:51], v[0:1], v[6:7] op_sel_hi:[1,0,1]
	ds_read2st64_b32 v[6:7], v206 offset0:6 offset1:7
	ds_read2st64_b32 v[10:11], v206 offset0:22 offset1:23
	s_waitcnt lgkmcnt(1)
	v_pk_fma_f32 v[8:9], v[36:37], v[0:1], v[6:7] op_sel_hi:[1,0,1]
	s_waitcnt lgkmcnt(0)
	v_pk_fma_f32 v[6:7], v[52:53], v[0:1], v[10:11] op_sel_hi:[1,0,1]
	ds_read2st64_b32 v[10:11], v206 offset0:8 offset1:9
	ds_read2st64_b32 v[14:15], v206 offset0:24 offset1:25
	s_waitcnt lgkmcnt(1)
	v_pk_fma_f32 v[12:13], v[38:39], v[0:1], v[10:11] op_sel_hi:[1,0,1]
	s_waitcnt lgkmcnt(0)
	v_pk_fma_f32 v[10:11], v[54:55], v[0:1], v[14:15] op_sel_hi:[1,0,1]
	ds_read2st64_b32 v[14:15], v206 offset0:10 offset1:11
	ds_read2st64_b32 v[16:17], v206 offset0:26 offset1:27
	s_waitcnt lgkmcnt(1)
	v_pk_fma_f32 v[18:19], v[40:41], v[0:1], v[14:15] op_sel_hi:[1,0,1]
	s_waitcnt lgkmcnt(0)
	v_pk_fma_f32 v[14:15], v[56:57], v[0:1], v[16:17] op_sel_hi:[1,0,1]
	ds_read2st64_b32 v[16:17], v206 offset0:12 offset1:13
	ds_read2st64_b32 v[22:23], v206 offset0:28 offset1:29
	s_waitcnt lgkmcnt(1)
	v_pk_fma_f32 v[20:21], v[42:43], v[0:1], v[16:17] op_sel_hi:[1,0,1]
	s_waitcnt lgkmcnt(0)
	v_pk_fma_f32 v[16:17], v[58:59], v[0:1], v[22:23] op_sel_hi:[1,0,1]
	ds_read2st64_b32 v[22:23], v206 offset0:14 offset1:15
	ds_read2st64_b32 v[26:27], v206 offset0:30 offset1:31
	s_waitcnt lgkmcnt(1)
	v_pk_fma_f32 v[24:25], v[44:45], v[0:1], v[22:23] op_sel_hi:[1,0,1]
	s_waitcnt lgkmcnt(0)
	v_pk_fma_f32 v[22:23], v[60:61], v[0:1], v[26:27] op_sel_hi:[1,0,1]
	ds_read2st64_b32 v[26:27], v206 offset0:16 offset1:17
	ds_read2st64_b32 v[30:31], v206 offset0:32 offset1:33
	s_waitcnt lgkmcnt(1)
	v_pk_fma_f32 v[28:29], v[46:47], v[0:1], v[26:27] op_sel_hi:[1,0,1]
	s_waitcnt lgkmcnt(0)
	v_pk_fma_f32 v[26:27], v[62:63], v[0:1], v[30:31] op_sel_hi:[1,0,1]
	ds_read2st64_b32 v[30:31], v206 offset0:18 offset1:19
	ds_read2st64_b32 v[34:35], v206 offset0:34 offset1:35
	s_waitcnt lgkmcnt(0)
	s_waitcnt lgkmcnt(1)
	v_pk_fma_f32 v[32:33], v[48:49], v[0:1], v[30:31] op_sel_hi:[1,0,1]
	s_waitcnt lgkmcnt(0)
	v_pk_fma_f32 v[30:31], v[64:65], v[0:1], v[34:35] op_sel_hi:[1,0,1]
	v_lshlrev_b64 v[34:35], 11, v[148:149]
	v_lshl_add_u64 v[34:35], s[0:1], 0, v[34:35]
	v_lshlrev_b32_e32 v0, 1, v207
	v_lshl_add_u64 v[34:35], v[34:35], 0, v[0:1]

.Lnsa_ready:
	s_lshr_b32 s2, s40, 1
	s_and_b32 s2, s2, 0xfc
	s_and_b32 s3, s40, 3
	s_or_b32 s2, s2, s3
	s_xor_b32 s86, s2, 0xfc
	s_lshr_b32 s0, s40, 9
	v_readlane_b32 s1, v254, 63
	s_lshl_b32 s89, s86, 3
	s_waitcnt vmcnt(3)
	v_bfe_u32 v129, v188, 2, 3
	s_or_b32 s0, s0, s1
	v_or_b32_e32 v197, s89, v129
	s_bfe_u32 s1, s40, 0x10002
	v_and_b32_e32 v130, 3, v188
	v_lshl_or_b32 v148, s0, 11, v197
	s_lshl_b32 s0, s0, 1
	v_lshl_or_b32 v128, s1, 2, v130
	s_or_b32 s36, s0, s1
	v_mov_b32_e32 v149, v1
	v_readlane_b32 s0, v254, 61
	v_lshlrev_b64 v[2:3], 10, v[148:149]
	v_readlane_b32 s1, v254, 62
	v_readlane_b32 s2, v254, 57
	v_lshlrev_b32_e32 v154, 3, v188
	v_lshl_add_u64 v[2:3], s[0:1], 0, v[2:3]
	s_lshl_b64 s[0:1], s[36:37], 14
	s_add_u32 s4, s2, s0
	v_readlane_b32 s2, v254, 55
	v_ashrrev_i32_e32 v155, 31, v154
	s_addc_u32 s5, s2, s1
	v_lshlrev_b64 v[152:153], 1, v[154:155]
	v_lshl_add_u64 v[42:43], s[4:5], 0, v[152:153]
	s_movk_i32 s2, 0x2000
	v_add_co_u32_e32 v46, vcc, s2, v42
	v_lshlrev_b32_e32 v0, 7, v128
	s_nop 0
	v_addc_co_u32_e32 v47, vcc, 0, v43, vcc
	v_lshl_add_u64 v[6:7], v[2:3], 0, v[0:1]
	global_load_dwordx4 v[2:5], v[46:47], off offset:-4096
	v_lshlrev_b32_e32 v8, 3, v196
	v_ashrrev_i32_e32 v9, 31, v8
	v_lshl_add_u64 v[52:53], v[8:9], 1, v[6:7]
	global_load_dwordx4 v[80:83], v[52:53], off
	global_load_dwordx4 v[18:21], v[42:43], off
	s_movk_i32 s3, 0x1000
	v_add_co_u32_e32 v50, vcc, s3, v42
	global_load_dwordx4 v[84:87], v[52:53], off offset:32
	s_nop 0
	v_addc_co_u32_e32 v51, vcc, 0, v43, vcc
	global_load_dwordx4 v[38:41], v[50:51], off offset:1024
	v_readlane_b32 s4, v254, 59
	v_readlane_b32 s5, v254, 60
	global_load_dwordx4 v[54:57], v[42:43], off offset:1024
	global_load_dwordx4 v[58:61], v[42:43], off offset:2048
	v_mov_b64_e32 v[6:7], s[4:5]
	s_movk_i32 s4, 0x60
	v_mad_u64_u32 v[6:7], s[4:5], v148, s4, v[6:7]
	v_readlane_b32 s4, v254, 53
	s_add_u32 s0, s4, s0
	v_readlane_b32 s4, v254, 51
	v_mul_u32_u24_e32 v0, 3, v128
	s_addc_u32 s1, s4, s1
	v_lshlrev_b32_e32 v0, 2, v0
	v_lshl_add_u64 v[48:49], s[0:1], 0, v[152:153]
	s_movk_i32 s0, 0x3000
	v_lshl_add_u64 v[150:151], v[6:7], 0, v[0:1]
	v_add_co_u32_e32 v44, vcc, s0, v48
	v_lshlrev_b32_e32 v66, 6, v196
	s_nop 0
	v_addc_co_u32_e32 v45, vcc, 0, v49, vcc
	global_load_dword v0, v[150:151], off
	global_load_dword v234, v[150:151], off offset:4
	global_load_dwordx4 v[34:37], v[44:45], off offset:3072
	global_load_dwordx4 v[88:91], v[52:53], off offset:64
	global_load_dwordx4 v[62:65], v[42:43], off offset:3072
	global_load_dwordx4 v[92:95], v[52:53], off offset:96
	v_or_b32_e32 v67, 31, v66
	v_or_b32_e32 v68, 47, v66
	v_cmp_le_i32_e32 vcc, v67, v197
	v_or_b32_e32 v69, 63, v66
	v_add_u32_e32 v70, 0x4f, v66
	v_add_u32_e32 v71, 0x9f, v66
	v_add_u32_e32 v72, 0xaf, v66
	v_add_u32_e32 v73, 0xbf, v66
	v_add_u32_e32 v74, 0xcf, v66
	v_add_u32_e32 v75, 0x19f, v66
	v_add_u32_e32 v76, 0x1af, v66
	v_lshl_add_u32 v206, v188, 2, s83
	v_cmp_eq_u32_e64 s[8:9], 0, v130
	s_waitcnt vmcnt(9)
	v_mfma_f32_32x32x16_bf16 v[18:33], v[18:21], v[80:83], 0
	v_mfma_f32_32x32x16_bf16 v[2:17], v[2:5], v[80:83], 0
	s_waitcnt vmcnt(7)
	v_mfma_f32_32x32x16_bf16 v[2:17], v[38:41], v[84:87], v[2:17]
	global_load_dwordx4 v[38:41], v[50:51], off offset:2048
	s_nop 0
	global_load_dwordx4 v[50:53], v[50:51], off offset:3072
	s_waitcnt vmcnt(8)
	v_mfma_f32_32x32x16_bf16 v[18:33], v[54:57], v[84:87], v[18:33]
	global_load_dwordx4 v[54:57], v[46:47], off
	s_waitcnt vmcnt(5)
	v_mfma_f32_32x32x16_bf16 v[18:33], v[58:61], v[88:91], v[18:33]
	v_add_u32_e32 v58, 0x11f, v66
	v_add_u32_e32 v59, 0x12f, v66
	v_add_u32_e32 v60, 0x13f, v66
	v_add_u32_e32 v61, 0x14f, v66
	s_waitcnt vmcnt(3)
	v_mfma_f32_32x32x16_bf16 v[18:33], v[62:65], v[92:95], v[18:33]
	s_waitcnt vmcnt(2)
	v_mfma_f32_32x32x16_bf16 v[2:17], v[38:41], v[88:91], v[2:17]
	s_nop 9
	v_mul_f32_e32 v18, 0x3e38aa3b, v18
	v_mul_f32_e32 v19, 0x3e38aa3b, v19
	v_cndmask_b32_e32 v62, v239, v18, vcc
	v_cmp_le_i32_e32 vcc, v68, v197
	v_mul_f32_e32 v20, 0x3e38aa3b, v20
	v_mul_f32_e32 v21, 0x3e38aa3b, v21
	v_cndmask_b32_e32 v63, v239, v19, vcc
	v_cmp_le_i32_e32 vcc, v69, v197
	v_mul_f32_e32 v22, 0x3e38aa3b, v22
	v_mul_f32_e32 v23, 0x3e38aa3b, v23
	v_cndmask_b32_e32 v64, v239, v20, vcc
	v_cmp_le_i32_e32 vcc, v70, v197
	v_mul_f32_e32 v24, 0x3e38aa3b, v24
	v_mul_f32_e32 v25, 0x3e38aa3b, v25
	v_cndmask_b32_e32 v65, v239, v21, vcc
	v_cmp_le_i32_e32 vcc, v71, v197
	v_mul_f32_e32 v26, 0x3e38aa3b, v26
	v_mul_f32_e32 v27, 0x3e38aa3b, v27
	v_cndmask_b32_e32 v67, v239, v22, vcc
	v_cmp_le_i32_e32 vcc, v72, v197
	v_mul_f32_e32 v28, 0x3e38aa3b, v28
	global_load_dwordx4 v[38:41], v[46:47], off offset:2048
	v_cndmask_b32_e32 v68, v239, v23, vcc
	v_cmp_le_i32_e32 vcc, v73, v197
	s_waitcnt vmcnt(2)
	v_mfma_f32_32x32x16_bf16 v[2:17], v[50:53], v[92:95], v[2:17]
	v_mul_f32_e32 v29, 0x3e38aa3b, v29
	v_cndmask_b32_e32 v69, v239, v24, vcc
	v_cmp_le_i32_e32 vcc, v74, v197
	v_mul_f32_e32 v30, 0x3e38aa3b, v30
	v_mul_f32_e32 v31, 0x3e38aa3b, v31
	v_cndmask_b32_e32 v70, v239, v25, vcc
	v_cmp_le_i32_e32 vcc, v58, v197
	v_add_u32_e32 v19, 0x1bf, v66
	global_load_dwordx4 v[50:53], v[46:47], off offset:3072
	v_cndmask_b32_e32 v71, v239, v26, vcc
	v_cmp_le_i32_e32 vcc, v59, v197
	v_mul_f32_e32 v20, 0x3e38aa3b, v32
	v_mul_f32_e32 v2, 0x3e38aa3b, v2
	v_cndmask_b32_e32 v72, v239, v27, vcc
	v_cmp_le_i32_e32 vcc, v60, v197
	v_max3_f32 v18, v62, s69, v63
	v_max3_f32 v18, v18, v64, v65
	v_cndmask_b32_e32 v73, v239, v28, vcc
	v_cmp_le_i32_e32 vcc, v61, v197
	global_load_dwordx4 v[58:61], v[46:47], off offset:1024
	v_mul_f32_e32 v3, 0x3e38aa3b, v3
	v_cndmask_b32_e32 v74, v239, v29, vcc
	v_cmp_le_i32_e32 vcc, v75, v197
	v_max3_f32 v18, v18, v67, v68
	v_max3_f32 v18, v18, v69, v70
	v_cndmask_b32_e32 v75, v239, v30, vcc
	v_cmp_le_i32_e32 vcc, v76, v197
	v_mul_f32_e32 v4, 0x3e38aa3b, v4
	v_max3_f32 v18, v18, v71, v72
	v_cndmask_b32_e32 v76, v239, v31, vcc
	v_cmp_le_i32_e32 vcc, v19, v197
	v_add_u32_e32 v19, 0x1cf, v66
	v_max3_f32 v18, v18, v73, v74
	v_cndmask_b32_e32 v77, v239, v20, vcc
	v_mul_f32_e32 v20, 0x3e38aa3b, v33
	v_cmp_le_i32_e32 vcc, v19, v197
	v_add_u32_e32 v19, 0x21f, v66
	v_max3_f32 v18, v18, v75, v76
	v_cndmask_b32_e32 v78, v239, v20, vcc
	v_cmp_le_i32_e32 vcc, v19, v197
	v_max3_f32 v18, v18, v77, v78
	s_nop 0
	v_cndmask_b32_e32 v46, v239, v2, vcc
	v_add_u32_e32 v2, 0x22f, v66
	v_cmp_le_i32_e32 vcc, v2, v197
	s_nop 1
	v_cndmask_b32_e32 v47, v239, v3, vcc
	v_add_u32_e32 v3, 0x23f, v66
	v_cmp_le_i32_e32 vcc, v3, v197
	v_add_u32_e32 v3, 0x24f, v66
	v_max3_f32 v2, v18, v46, v47
	v_cndmask_b32_e32 v96, v239, v4, vcc
	v_mul_f32_e32 v4, 0x3e38aa3b, v5
	v_cmp_le_i32_e32 vcc, v3, v197
	v_add_u32_e32 v3, 0x29f, v66
	s_waitcnt vmcnt(3)
	v_mfma_f32_32x32x16_bf16 v[18:33], v[54:57], v[80:83], 0
	v_cndmask_b32_e32 v97, v239, v4, vcc
	v_mul_f32_e32 v4, 0x3e38aa3b, v6
	v_cmp_le_i32_e32 vcc, v3, v197
	v_add_u32_e32 v3, 0x2af, v66
	v_max3_f32 v2, v2, v96, v97
	v_cndmask_b32_e32 v100, v239, v4, vcc
	v_mul_f32_e32 v4, 0x3e38aa3b, v7
	v_cmp_le_i32_e32 vcc, v3, v197
	v_add_u32_e32 v3, 0x2bf, v66
	s_waitcnt vmcnt(0)
	v_mfma_f32_32x32x16_bf16 v[18:33], v[58:61], v[84:87], v[18:33]
	v_cndmask_b32_e32 v101, v239, v4, vcc
	v_mul_f32_e32 v4, 0x3e38aa3b, v8
	v_cmp_le_i32_e32 vcc, v3, v197
	v_add_u32_e32 v3, 0x2cf, v66
	v_max3_f32 v2, v2, v100, v101
	v_cndmask_b32_e32 v102, v239, v4, vcc
	v_mul_f32_e32 v4, 0x3e38aa3b, v9
	v_cmp_le_i32_e32 vcc, v3, v197
	v_add_u32_e32 v3, 0x31f, v66
	v_mfma_f32_32x32x16_bf16 v[18:33], v[38:41], v[88:91], v[18:33]
	v_cndmask_b32_e32 v103, v239, v4, vcc
	v_mul_f32_e32 v4, 0x3e38aa3b, v10
	v_cmp_le_i32_e32 vcc, v3, v197
	v_add_u32_e32 v3, 0x32f, v66
	v_max3_f32 v2, v2, v102, v103
	v_cndmask_b32_e32 v104, v239, v4, vcc
	v_mul_f32_e32 v4, 0x3e38aa3b, v11
	v_cmp_le_i32_e32 vcc, v3, v197
	v_mul_f32_e32 v3, 0x3e38aa3b, v12
	v_mfma_f32_32x32x16_bf16 v[18:33], v[50:53], v[92:95], v[18:33]
	v_cndmask_b32_e32 v105, v239, v4, vcc
	v_max3_f32 v8, v2, v104, v105
	v_add_u32_e32 v2, 0x33f, v66
	v_cmp_le_i32_e32 vcc, v2, v197
	v_add_u32_e32 v2, 0x34f, v66
	v_add_u32_e32 v9, 0x39f, v66
	v_cndmask_b32_e32 v106, v239, v3, vcc
	v_mul_f32_e32 v3, 0x3e38aa3b, v13
	v_cmp_le_i32_e32 vcc, v2, v197
	v_mul_f32_e32 v10, 0x3e38aa3b, v14
	s_nop 1
	v_mul_f32_e32 v29, 0x3e38aa3b, v29
	v_cndmask_b32_e32 v107, v239, v3, vcc
	v_add_co_u32_e32 v6, vcc, s0, v42
	v_max3_f32 v8, v8, v106, v107
	s_nop 0
	v_addc_co_u32_e32 v7, vcc, 0, v43, vcc
	global_load_dwordx4 v[2:5], v[6:7], off
	global_load_dwordx4 v[54:57], v[6:7], off offset:1024
	global_load_dwordx4 v[58:61], v[6:7], off offset:2048
	global_load_dwordx4 v[38:41], v[6:7], off offset:3072
	v_cmp_le_i32_e32 vcc, v9, v197
	v_add_u32_e32 v9, 0x3af, v66
	v_add_u32_e32 v7, 0x41f, v66
	v_cndmask_b32_e32 v108, v239, v10, vcc
	v_mul_f32_e32 v10, 0x3e38aa3b, v15
	v_cmp_le_i32_e32 vcc, v9, v197
	v_add_u32_e32 v9, 0x3bf, v66
	v_mul_f32_e32 v30, 0x3e38aa3b, v30
	v_cndmask_b32_e32 v109, v239, v10, vcc
	v_mul_f32_e32 v10, 0x3e38aa3b, v16
	v_cmp_le_i32_e32 vcc, v9, v197
	v_add_u32_e32 v9, 0x3cf, v66
	v_max3_f32 v8, v8, v108, v109
	v_cndmask_b32_e32 v110, v239, v10, vcc
	v_mul_f32_e32 v10, 0x3e38aa3b, v17
	v_cmp_le_i32_e32 vcc, v9, v197
	v_mul_f32_e32 v31, 0x3e38aa3b, v31
	v_mul_f32_e32 v32, 0x3e38aa3b, v32
	v_cndmask_b32_e32 v111, v239, v10, vcc
	v_max3_f32 v6, v8, v110, v111
	v_mul_f32_e32 v8, 0x3e38aa3b, v18
	v_cmp_le_i32_e32 vcc, v7, v197
	v_add_u32_e32 v7, 0x42f, v66
	v_mul_f32_e32 v33, 0x3e38aa3b, v33
	v_cndmask_b32_e32 v50, v239, v8, vcc
	v_mul_f32_e32 v8, 0x3e38aa3b, v19
	v_cmp_le_i32_e32 vcc, v7, v197
	v_add_u32_e32 v7, 0x43f, v66
	v_add_u32_e32 v19, 0x54f, v66
	v_cndmask_b32_e32 v51, v239, v8, vcc
	v_mul_f32_e32 v8, 0x3e38aa3b, v20
	v_cmp_le_i32_e32 vcc, v7, v197
	v_add_u32_e32 v7, 0x44f, v66
	v_max3_f32 v6, v6, v50, v51
	v_cndmask_b32_e32 v20, v239, v8, vcc
	v_mul_f32_e32 v8, 0x3e38aa3b, v21
	v_cmp_le_i32_e32 vcc, v7, v197
	v_add_u32_e32 v7, 0x49f, v66
	s_nop 0
	v_cndmask_b32_e32 v21, v239, v8, vcc
	v_mul_f32_e32 v8, 0x3e38aa3b, v22
	v_cmp_le_i32_e32 vcc, v7, v197
	v_add_u32_e32 v7, 0x4af, v66
	v_max3_f32 v6, v6, v20, v21
	v_cndmask_b32_e32 v22, v239, v8, vcc
	v_mul_f32_e32 v8, 0x3e38aa3b, v23
	v_cmp_le_i32_e32 vcc, v7, v197
	v_add_u32_e32 v7, 0x4bf, v66
	s_nop 0
	v_cndmask_b32_e32 v23, v239, v8, vcc
	v_mul_f32_e32 v8, 0x3e38aa3b, v24
	v_cmp_le_i32_e32 vcc, v7, v197
	v_add_u32_e32 v7, 0x4cf, v66
	v_max3_f32 v6, v6, v22, v23
	v_cndmask_b32_e32 v24, v239, v8, vcc
	v_mul_f32_e32 v8, 0x3e38aa3b, v25
	v_cmp_le_i32_e32 vcc, v7, v197
	v_add_u32_e32 v7, 0x51f, v66
	s_nop 0
	v_cndmask_b32_e32 v25, v239, v8, vcc
	v_mul_f32_e32 v8, 0x3e38aa3b, v26
	v_cmp_le_i32_e32 vcc, v7, v197
	v_add_u32_e32 v7, 0x52f, v66
	v_max3_f32 v6, v6, v24, v25
	v_cndmask_b32_e32 v26, v239, v8, vcc
	v_mul_f32_e32 v8, 0x3e38aa3b, v27
	v_cmp_le_i32_e32 vcc, v7, v197
	v_mul_f32_e32 v7, 0x3e38aa3b, v28
	s_nop 0
	v_cndmask_b32_e32 v27, v239, v8, vcc
	v_max3_f32 v18, v6, v26, v27
	v_add_u32_e32 v6, 0x53f, v66
	v_cmp_le_i32_e32 vcc, v6, v197
	s_nop 1
	v_cndmask_b32_e32 v28, v239, v7, vcc
	s_waitcnt vmcnt(3)
	v_mfma_f32_32x32x16_bf16 v[2:17], v[2:5], v[80:83], 0
	v_cmp_le_i32_e32 vcc, v19, v197
	v_add_u32_e32 v19, 0x59f, v66
	s_nop 0
	v_cndmask_b32_e32 v29, v239, v29, vcc
	v_cmp_le_i32_e32 vcc, v19, v197
	v_add_u32_e32 v19, 0x5af, v66
	v_max3_f32 v18, v18, v28, v29
	s_waitcnt vmcnt(2)
	v_mfma_f32_32x32x16_bf16 v[2:17], v[54:57], v[84:87], v[2:17]
	v_cndmask_b32_e32 v30, v239, v30, vcc
	v_cmp_le_i32_e32 vcc, v19, v197
	v_add_u32_e32 v19, 0x5bf, v66
	s_nop 0
	v_cndmask_b32_e32 v31, v239, v31, vcc
	v_cmp_le_i32_e32 vcc, v19, v197
	v_add_u32_e32 v19, 0x5cf, v66
	s_waitcnt vmcnt(1)
	v_mfma_f32_32x32x16_bf16 v[2:17], v[58:61], v[88:91], v[2:17]
	v_cndmask_b32_e32 v32, v239, v32, vcc
	v_cmp_le_i32_e32 vcc, v19, v197
	v_add_u32_e32 v19, 0x61f, v66
	v_max3_f32 v18, v18, v30, v31
	v_cndmask_b32_e32 v33, v239, v33, vcc
	v_cmp_le_i32_e32 vcc, v19, v197
	v_max3_f32 v18, v18, v32, v33
	s_waitcnt vmcnt(0)
	v_mfma_f32_32x32x16_bf16 v[2:17], v[38:41], v[92:95], v[2:17]
	s_nop 11
	v_mul_f32_e32 v2, 0x3e38aa3b, v2
	v_cndmask_b32_e32 v114, v239, v2, vcc
	v_add_u32_e32 v2, 0x62f, v66
	v_mul_f32_e32 v3, 0x3e38aa3b, v3
	v_cmp_le_i32_e32 vcc, v2, v197
	v_mul_f32_e32 v4, 0x3e38aa3b, v4
	s_nop 0
	v_cndmask_b32_e32 v115, v239, v3, vcc
	v_add_u32_e32 v3, 0x63f, v66
	v_cmp_le_i32_e32 vcc, v3, v197
	v_add_u32_e32 v3, 0x64f, v66
	v_max3_f32 v2, v18, v114, v115
	v_cndmask_b32_e32 v116, v239, v4, vcc
	v_mul_f32_e32 v4, 0x3e38aa3b, v5
	v_cmp_le_i32_e32 vcc, v3, v197
	v_add_u32_e32 v3, 0x69f, v66
	s_nop 0
	v_cndmask_b32_e32 v117, v239, v4, vcc
	v_mul_f32_e32 v4, 0x3e38aa3b, v6
	v_cmp_le_i32_e32 vcc, v3, v197
	v_add_u32_e32 v3, 0x6af, v66
	v_max3_f32 v2, v2, v116, v117
	v_cndmask_b32_e32 v120, v239, v4, vcc
	v_mul_f32_e32 v4, 0x3e38aa3b, v7
	v_cmp_le_i32_e32 vcc, v3, v197
	v_add_u32_e32 v3, 0x6bf, v66
	s_nop 0
	v_cndmask_b32_e32 v121, v239, v4, vcc
	v_mul_f32_e32 v4, 0x3e38aa3b, v8
	v_cmp_le_i32_e32 vcc, v3, v197
	v_add_u32_e32 v3, 0x6cf, v66
	v_max3_f32 v2, v2, v120, v121
	v_cndmask_b32_e32 v122, v239, v4, vcc
	v_mul_f32_e32 v4, 0x3e38aa3b, v9
	v_cmp_le_i32_e32 vcc, v3, v197
	v_add_u32_e32 v3, 0x71f, v66
	s_nop 0
	v_cndmask_b32_e32 v123, v239, v4, vcc
	v_mul_f32_e32 v4, 0x3e38aa3b, v10
	v_cmp_le_i32_e32 vcc, v3, v197
	v_add_u32_e32 v3, 0x72f, v66
	v_max3_f32 v2, v2, v122, v123
	v_cndmask_b32_e32 v132, v239, v4, vcc
	v_mul_f32_e32 v4, 0x3e38aa3b, v11
	v_cmp_le_i32_e32 vcc, v3, v197
	v_add_u32_e32 v3, 0x73f, v66
	s_nop 0
	v_cndmask_b32_e32 v133, v239, v4, vcc
	v_mul_f32_e32 v4, 0x3e38aa3b, v12
	v_cmp_le_i32_e32 vcc, v3, v197
	v_add_u32_e32 v3, 0x74f, v66
	v_max3_f32 v2, v2, v132, v133
	v_cndmask_b32_e32 v134, v239, v4, vcc
	v_mul_f32_e32 v4, 0x3e38aa3b, v13
	v_cmp_le_i32_e32 vcc, v3, v197
	v_add_u32_e32 v3, 0x79f, v66
	s_nop 0
	v_cndmask_b32_e32 v135, v239, v4, vcc
	v_mul_f32_e32 v4, 0x3e38aa3b, v14
	v_cmp_le_i32_e32 vcc, v3, v197
	v_add_u32_e32 v3, 0x7af, v66
	v_max3_f32 v2, v2, v134, v135
	v_cndmask_b32_e32 v14, v239, v4, vcc
	v_mul_f32_e32 v4, 0x3e38aa3b, v15
	v_cmp_le_i32_e32 vcc, v3, v197
	v_add_u32_e32 v3, 0x7bf, v66
	s_nop 0
	v_cndmask_b32_e32 v15, v239, v4, vcc
	v_mul_f32_e32 v4, 0x3e38aa3b, v16
	v_cmp_le_i32_e32 vcc, v3, v197
	v_add_u32_e32 v3, 0x7cf, v66
	v_max3_f32 v2, v2, v14, v15
	v_cndmask_b32_e32 v16, v239, v4, vcc
	v_mul_f32_e32 v4, 0x3e38aa3b, v17
	v_cmp_le_i32_e32 vcc, v3, v197
	v_xor_b32_e32 v3, 32, v235
	s_nop 0
	v_cndmask_b32_e32 v17, v239, v4, vcc
	v_and_b32_e32 v4, 64, v235
	v_add_u32_e32 v131, 64, v4
	v_cmp_lt_i32_e32 vcc, v3, v131
	v_max3_f32 v2, v2, v16, v17
	s_nop 0
	v_cndmask_b32_e32 v3, v235, v3, vcc
	v_lshlrev_b32_e32 v205, 2, v3
	ds_bpermute_b32 v3, v205, v2
	s_waitcnt lgkmcnt(0)
	v_max_f32_e32 v3, v3, v3
	v_max_f32_e32 v2, v2, v3
	v_cmp_neq_f32_e32 vcc, s69, v2
	s_nop 1
	v_cndmask_b32_e32 v136, 0, v2, vcc
	v_sub_f32_e32 v2, v62, v136
	v_exp_f32_e32 v2, v2
	v_sub_f32_e32 v3, v63, v136
	v_exp_f32_e32 v3, v3
	v_sub_f32_e32 v4, v64, v136
	v_exp_f32_e32 v4, v4
	v_sub_f32_e32 v5, v65, v136
	v_exp_f32_e32 v5, v5
	v_add_f32_e32 v6, 0, v2
	v_add_f32_e32 v6, v3, v6
	v_add_f32_e32 v6, v4, v6
	v_add_f32_e32 v10, v5, v6
	v_sub_f32_e32 v6, v67, v136
	v_exp_f32_e32 v6, v6
	v_sub_f32_e32 v7, v68, v136
	v_exp_f32_e32 v7, v7
	v_sub_f32_e32 v8, v69, v136
	v_exp_f32_e32 v8, v8
	v_sub_f32_e32 v9, v70, v136
	v_exp_f32_e32 v9, v9
	v_sub_f32_e32 v11, v71, v136
	v_add_f32_e32 v10, v6, v10
	v_exp_f32_e32 v18, v11
	v_sub_f32_e32 v11, v72, v136
	v_add_f32_e32 v10, v7, v10
	v_exp_f32_e32 v19, v11
	v_sub_f32_e32 v11, v73, v136
	v_add_f32_e32 v10, v8, v10
	v_exp_f32_e32 v38, v11
	v_sub_f32_e32 v11, v74, v136
	v_add_f32_e32 v10, v9, v10
	v_exp_f32_e32 v39, v11
	v_sub_f32_e32 v11, v75, v136
	v_add_f32_e32 v10, v18, v10
	v_exp_f32_e32 v58, v11
	v_sub_f32_e32 v11, v76, v136
	v_add_f32_e32 v10, v19, v10
	v_exp_f32_e32 v59, v11
	v_sub_f32_e32 v11, v77, v136
	v_add_f32_e32 v10, v38, v10
	v_exp_f32_e32 v60, v11
	v_sub_f32_e32 v11, v78, v136
	v_add_f32_e32 v10, v39, v10
	v_exp_f32_e32 v61, v11
	v_sub_f32_e32 v11, v46, v136
	v_add_f32_e32 v10, v58, v10
	v_exp_f32_e32 v78, v11
	v_sub_f32_e32 v11, v47, v136
	v_add_f32_e32 v10, v59, v10
	v_exp_f32_e32 v79, v11
	v_sub_f32_e32 v11, v96, v136
	v_add_f32_e32 v10, v60, v10
	v_exp_f32_e32 v98, v11
	v_sub_f32_e32 v11, v97, v136
	v_add_f32_e32 v10, v61, v10
	v_exp_f32_e32 v99, v11
	v_sub_f32_e32 v11, v100, v136
	v_add_f32_e32 v10, v78, v10
	v_exp_f32_e32 v126, v11
	v_sub_f32_e32 v11, v101, v136
	v_add_f32_e32 v10, v79, v10
	v_exp_f32_e32 v127, v11
	v_sub_f32_e32 v11, v102, v136
	v_add_f32_e32 v10, v98, v10
	v_exp_f32_e32 v62, v11
	v_sub_f32_e32 v11, v103, v136
	v_add_f32_e32 v10, v99, v10
	v_exp_f32_e32 v63, v11
	v_sub_f32_e32 v11, v104, v136
	v_add_f32_e32 v10, v126, v10
	v_exp_f32_e32 v42, v11
	v_sub_f32_e32 v11, v105, v136
	v_add_f32_e32 v10, v127, v10
	v_exp_f32_e32 v43, v11
	v_sub_f32_e32 v11, v106, v136
	v_add_f32_e32 v10, v62, v10
	v_exp_f32_e32 v54, v11
	v_sub_f32_e32 v11, v107, v136
	v_add_f32_e32 v10, v63, v10
	v_exp_f32_e32 v55, v11
	v_sub_f32_e32 v11, v108, v136
	v_add_f32_e32 v10, v42, v10
	v_exp_f32_e32 v96, v11
	v_sub_f32_e32 v11, v109, v136
	v_add_f32_e32 v10, v43, v10
	v_exp_f32_e32 v97, v11
	v_sub_f32_e32 v11, v110, v136
	v_add_f32_e32 v10, v54, v10
	v_exp_f32_e32 v124, v11
	v_sub_f32_e32 v11, v111, v136
	v_add_f32_e32 v10, v55, v10
	v_exp_f32_e32 v125, v11
	v_sub_f32_e32 v11, v50, v136
	v_add_f32_e32 v10, v96, v10
	v_exp_f32_e32 v50, v11
	v_sub_f32_e32 v11, v51, v136
	v_add_f32_e32 v10, v97, v10
	v_exp_f32_e32 v51, v11
	v_sub_f32_e32 v11, v20, v136
	v_add_f32_e32 v10, v124, v10
	v_exp_f32_e32 v76, v11
	v_sub_f32_e32 v11, v21, v136
	v_add_f32_e32 v10, v125, v10
	v_exp_f32_e32 v77, v11
	v_sub_f32_e32 v11, v22, v136
	v_add_f32_e32 v10, v50, v10
	v_exp_f32_e32 v52, v11
	v_sub_f32_e32 v11, v23, v136
	v_add_f32_e32 v10, v51, v10
	v_exp_f32_e32 v53, v11
	v_sub_f32_e32 v11, v24, v136
	v_add_f32_e32 v10, v76, v10
	v_exp_f32_e32 v56, v11
	v_sub_f32_e32 v11, v25, v136
	v_add_f32_e32 v10, v77, v10
	v_exp_f32_e32 v57, v11
	v_sub_f32_e32 v11, v26, v136
	v_add_f32_e32 v10, v52, v10
	v_exp_f32_e32 v40, v11
	v_sub_f32_e32 v11, v27, v136
	v_add_f32_e32 v10, v53, v10
	v_exp_f32_e32 v41, v11
	v_sub_f32_e32 v11, v28, v136
	v_add_f32_e32 v10, v56, v10
	v_exp_f32_e32 v46, v11
	v_sub_f32_e32 v11, v29, v136
	v_add_f32_e32 v10, v57, v10
	v_exp_f32_e32 v47, v11
	v_sub_f32_e32 v11, v30, v136
	v_add_f32_e32 v10, v40, v10
	v_exp_f32_e32 v112, v11
	v_sub_f32_e32 v11, v31, v136
	v_add_f32_e32 v10, v41, v10
	v_exp_f32_e32 v113, v11
	v_sub_f32_e32 v11, v32, v136
	v_add_f32_e32 v10, v46, v10
	v_exp_f32_e32 v118, v11
	v_sub_f32_e32 v11, v33, v136
	v_add_f32_e32 v10, v47, v10
	v_exp_f32_e32 v119, v11
	v_add_f32_e32 v10, v112, v10
	v_add_f32_e32 v10, v113, v10
	v_add_f32_e32 v10, v118, v10
	v_add_f32_e32 v20, v119, v10
	v_sub_f32_e32 v10, v114, v136
	v_exp_f32_e32 v64, v10
	v_sub_f32_e32 v10, v115, v136
	v_sub_f32_e32 v21, v116, v136
	v_exp_f32_e32 v65, v10
	global_load_dwordx4 v[10:13], v[48:49], off
	v_exp_f32_e32 v72, v21
	v_sub_f32_e32 v21, v117, v136
	v_exp_f32_e32 v73, v21
	v_sub_f32_e32 v21, v120, v136
	v_exp_f32_e32 v66, v21
	v_sub_f32_e32 v21, v121, v136
	v_exp_f32_e32 v67, v21
	v_sub_f32_e32 v21, v122, v136
	v_exp_f32_e32 v74, v21
	v_sub_f32_e32 v21, v123, v136
	v_exp_f32_e32 v75, v21
	v_sub_f32_e32 v21, v132, v136
	v_exp_f32_e32 v68, v21
	v_sub_f32_e32 v21, v133, v136
	v_exp_f32_e32 v69, v21
	v_sub_f32_e32 v21, v134, v136
	v_exp_f32_e32 v70, v21
	v_sub_f32_e32 v21, v135, v136
	global_load_dwordx4 v[132:135], v[48:49], off offset:2048
	v_add_f32_e32 v20, v64, v20
	v_add_f32_e32 v20, v65, v20
	v_add_f32_e32 v20, v72, v20
	v_add_f32_e32 v20, v73, v20
	v_add_f32_e32 v20, v66, v20
	v_add_f32_e32 v20, v67, v20
	v_add_f32_e32 v20, v74, v20
	v_add_f32_e32 v20, v75, v20
	v_exp_f32_e32 v71, v21
	v_sub_f32_e32 v14, v14, v136
	v_add_f32_e32 v20, v68, v20
	v_exp_f32_e32 v102, v14
	v_sub_f32_e32 v14, v15, v136
	v_add_f32_e32 v20, v69, v20
	v_exp_f32_e32 v103, v14
	v_sub_f32_e32 v14, v16, v136
	v_add_f32_e32 v20, v70, v20
	v_exp_f32_e32 v106, v14
	v_sub_f32_e32 v14, v17, v136
	v_add_f32_e32 v20, v71, v20
	v_exp_f32_e32 v107, v14
	v_add_f32_e32 v14, v102, v20
	v_add_f32_e32 v14, v103, v14
	v_add_f32_e32 v14, v106, v14
	v_add_f32_e32 v14, v107, v14
	ds_bpermute_b32 v15, v205, v14
	global_load_dwordx4 v[20:23], v[48:49], off offset:1024
	global_load_dwordx4 v[136:139], v[48:49], off offset:3072
	s_waitcnt lgkmcnt(0)
	v_add_f32_e32 v14, v14, v15
	v_max_f32_e32 v14, 0xda24260, v14
	v_div_scale_f32 v15, s[0:1], v14, v14, 1.0
	v_rcp_f32_e32 v16, v15
	s_nop 0
	v_fma_f32 v17, -v15, v16, 1.0
	v_fmac_f32_e32 v16, v17, v16
	v_div_scale_f32 v17, vcc, 1.0, v14, 1.0
	v_mul_f32_e32 v24, v17, v16
	v_fma_f32 v25, -v15, v24, v17
	v_fmac_f32_e32 v24, v25, v16
	v_fma_f32 v15, -v15, v24, v17
	v_div_fmas_f32 v15, v15, v16, v24
	v_div_fixup_f32 v156, v15, v14, 1.0
	v_pk_mul_f32 v[120:121], v[2:3], v[156:157] op_sel_hi:[1,0]
	v_pk_mul_f32 v[122:123], v[4:5], v[156:157] op_sel_hi:[1,0]
	v_pk_mul_f32 v[110:111], v[6:7], v[156:157] op_sel_hi:[1,0]
	v_pk_mul_f32 v[116:117], v[8:9], v[156:157] op_sel_hi:[1,0]
	v_cvt_pk_bf16_f32 v24, v120, v121
	v_cvt_pk_bf16_f32 v25, v122, v123
	v_cvt_pk_bf16_f32 v26, v110, v111
	v_cvt_pk_bf16_f32 v27, v116, v117
	v_add_co_u32_e32 v158, vcc, s2, v48
	s_waitcnt vmcnt(3)
	v_mfma_f32_32x32x16_bf16 v[2:17], v[10:13], v[24:27], 0
	v_addc_co_u32_e32 v159, vcc, 0, v49, vcc
	v_mul_f32_e64 v108, v18, v156
	v_mul_f32_e64 v109, v19, v156
	v_mul_f32_e64 v114, v38, v156
	v_mul_f32_e64 v115, v39, v156
	v_pk_mul_f32 v[100:101], v[58:59], v[156:157] op_sel_hi:[1,0]
	v_pk_mul_f32 v[104:105], v[60:61], v[156:157] op_sel_hi:[1,0]
	v_add_co_u32_e32 v160, vcc, s3, v48
	v_cvt_pk_bf16_f32 v144, v108, v109
	v_cvt_pk_bf16_f32 v145, v114, v115
	v_cvt_pk_bf16_f32 v146, v100, v101
	v_cvt_pk_bf16_f32 v147, v104, v105
	v_addc_co_u32_e32 v161, vcc, 0, v49, vcc
	global_load_dwordx4 v[140:143], v[158:159], off offset:-4096
	s_waitcnt vmcnt(3)
	v_mfma_f32_32x32x16_bf16 v[2:17], v[132:135], v[144:147], v[2:17]
	global_load_dwordx4 v[132:135], v[160:161], off offset:1024
	v_mul_f32_e64 v58, v78, v156
	v_mul_f32_e64 v59, v79, v156
	v_mul_f32_e64 v60, v98, v156
	v_mul_f32_e64 v61, v99, v156
	v_pk_mul_f32 v[38:39], v[126:127], v[156:157] op_sel_hi:[1,0]
	v_pk_mul_f32 v[62:63], v[62:63], v[156:157] op_sel_hi:[1,0]
	v_pk_mul_f32 v[78:79], v[42:43], v[156:157] op_sel_hi:[1,0]
	v_pk_mul_f32 v[98:99], v[54:55], v[156:157] op_sel_hi:[1,0]
	s_waitcnt vmcnt(3)
	v_mfma_f32_32x32x16_bf16 v[18:33], v[20:23], v[24:27], 0
	v_mul_f32_e64 v42, v96, v156
	v_mul_f32_e64 v43, v97, v156
	v_mul_f32_e64 v48, v124, v156
	v_mul_f32_e64 v49, v125, v156
	v_cvt_pk_bf16_f32 v124, v78, v79
	v_cvt_pk_bf16_f32 v125, v98, v99
	v_cvt_pk_bf16_f32 v126, v42, v43
	v_cvt_pk_bf16_f32 v127, v48, v49
	v_pk_mul_f32 v[50:51], v[50:51], v[156:157] op_sel_hi:[1,0]
	s_waitcnt vmcnt(2)
	v_mfma_f32_32x32x16_bf16 v[18:33], v[136:139], v[144:147], v[18:33]
	v_cvt_pk_bf16_f32 v136, v58, v59
	v_cvt_pk_bf16_f32 v137, v60, v61
	v_cvt_pk_bf16_f32 v138, v38, v39
	v_cvt_pk_bf16_f32 v139, v62, v63
	global_load_dwordx4 v[144:147], v[158:159], off
	v_pk_mul_f32 v[54:55], v[76:77], v[156:157] op_sel_hi:[1,0]
	v_pk_mul_f32 v[52:53], v[52:53], v[156:157] op_sel_hi:[1,0]
	s_waitcnt vmcnt(2)
	v_mfma_f32_32x32x16_bf16 v[2:17], v[140:143], v[136:139], v[2:17]
	global_load_dwordx4 v[140:143], v[160:161], off offset:2048
	v_mul_f32_e64 v56, v56, v156
	v_mul_f32_e64 v57, v57, v156
	v_mul_f32_e64 v76, v40, v156
	v_mul_f32_e64 v77, v41, v156
	v_pk_mul_f32 v[96:97], v[46:47], v[156:157] op_sel_hi:[1,0]
	v_pk_mul_f32 v[40:41], v[112:113], v[156:157] op_sel_hi:[1,0]
	v_pk_mul_f32 v[46:47], v[118:119], v[156:157] op_sel_hi:[1,0]
	v_pk_mul_f32 v[64:65], v[64:65], v[156:157] op_sel_hi:[1,0]
	s_waitcnt vmcnt(2)
	v_mfma_f32_32x32x16_bf16 v[18:33], v[132:135], v[136:139], v[18:33]
	global_load_dwordx4 v[132:135], v[160:161], off offset:3072
	global_load_dwordx4 v[136:139], v[44:45], off
	v_mul_f32_e64 v72, v72, v156
	v_mul_f32_e64 v73, v73, v156
	v_mul_f32_e64 v66, v66, v156
	v_mul_f32_e64 v67, v67, v156
	v_pk_mul_f32 v[74:75], v[74:75], v[156:157] op_sel_hi:[1,0]
	v_pk_mul_f32 v[112:113], v[68:69], v[156:157] op_sel_hi:[1,0]
	v_pk_mul_f32 v[70:71], v[70:71], v[156:157] op_sel_hi:[1,0]
	s_waitcnt vmcnt(2)
	v_mfma_f32_32x32x16_bf16 v[2:17], v[140:143], v[124:127], v[2:17]
	global_load_dwordx4 v[140:143], v[158:159], off offset:2048
	v_mul_f32_e64 v68, v106, v156
	v_mul_f32_e64 v69, v107, v156
	s_waitcnt vmcnt(2)
	v_mfma_f32_32x32x16_bf16 v[18:33], v[132:135], v[124:127], v[18:33]
	global_load_dwordx4 v[124:127], v[158:159], off offset:1024
	v_cvt_pk_bf16_f32 v132, v50, v51
	v_cvt_pk_bf16_f32 v133, v54, v55
	v_cvt_pk_bf16_f32 v134, v52, v53
	v_cvt_pk_bf16_f32 v135, v56, v57
	s_nop 1
	v_mfma_f32_32x32x16_bf16 v[2:17], v[144:147], v[132:135], v[2:17]
	s_waitcnt vmcnt(0)
	v_mfma_f32_32x32x16_bf16 v[18:33], v[124:127], v[132:135], v[18:33]
	global_load_dwordx4 v[132:135], v[158:159], off offset:3072
	v_cvt_pk_bf16_f32 v124, v76, v77
	v_cvt_pk_bf16_f32 v125, v96, v97
	v_cvt_pk_bf16_f32 v126, v40, v41
	v_cvt_pk_bf16_f32 v127, v46, v47
	s_nop 1
	v_mfma_f32_32x32x16_bf16 v[2:17], v[140:143], v[124:127], v[2:17]
	s_waitcnt vmcnt(0)
	v_mfma_f32_32x32x16_bf16 v[18:33], v[132:135], v[124:127], v[18:33]
	global_load_dwordx4 v[124:127], v[44:45], off offset:1024
	v_cvt_pk_bf16_f32 v132, v64, v65
	v_cvt_pk_bf16_f32 v133, v72, v73
	v_cvt_pk_bf16_f32 v134, v66, v67
	v_cvt_pk_bf16_f32 v135, v74, v75
	s_nop 1
	v_mfma_f32_32x32x16_bf16 v[2:17], v[136:139], v[132:135], v[2:17]
	global_load_dwordx4 v[136:139], v[44:45], off offset:2048
	v_mul_f32_e64 v44, v102, v156
	v_mul_f32_e64 v45, v103, v156
	s_waitcnt vmcnt(1)
	v_mfma_f32_32x32x16_bf16 v[18:33], v[124:127], v[132:135], v[18:33]
	v_cvt_pk_bf16_f32 v124, v112, v113
	v_cvt_pk_bf16_f32 v125, v70, v71
	v_cvt_pk_bf16_f32 v126, v44, v45
	v_cvt_pk_bf16_f32 v127, v68, v69
	s_waitcnt vmcnt(0)
	s_nop 0
	v_mfma_f32_32x32x16_bf16 v[2:17], v[136:139], v[124:127], v[2:17]
	v_mfma_f32_32x32x16_bf16 v[18:33], v[34:37], v[124:127], v[18:33]
	s_nop 10
	v_mul_f32_e32 v2, v0, v2
	v_mul_f32_e32 v3, v0, v3
	ds_write2st64_b32 v206, v2, v3 offset0:4 offset1:5
	v_mul_f32_e32 v18, v0, v18
	v_mul_f32_e32 v2, v0, v19
	ds_write2st64_b32 v206, v18, v2 offset0:20 offset1:21
	v_mul_f32_e32 v2, v0, v4
	v_mul_f32_e32 v4, v0, v5
	v_mul_f32_e32 v3, v0, v20
	ds_write2st64_b32 v206, v2, v4 offset0:6 offset1:7
	v_mul_f32_e32 v2, v0, v21
	ds_write2st64_b32 v206, v3, v2 offset0:22 offset1:23
	v_mul_f32_e32 v2, v0, v6
	v_mul_f32_e32 v4, v0, v7
	v_mul_f32_e32 v3, v0, v22
	ds_write2st64_b32 v206, v2, v4 offset0:8 offset1:9
	v_mul_f32_e32 v2, v0, v23
	ds_write2st64_b32 v206, v3, v2 offset0:24 offset1:25
	v_mul_f32_e32 v2, v0, v8
	v_mul_f32_e32 v4, v0, v9
	v_mul_f32_e32 v3, v0, v24
	ds_write2st64_b32 v206, v2, v4 offset0:10 offset1:11
	v_mul_f32_e32 v2, v0, v25
	ds_write2st64_b32 v206, v3, v2 offset0:26 offset1:27
	v_mul_f32_e32 v2, v0, v10
	v_mul_f32_e32 v4, v0, v11
	v_mul_f32_e32 v3, v0, v26
	ds_write2st64_b32 v206, v2, v4 offset0:12 offset1:13
	v_mul_f32_e32 v2, v0, v27
	ds_write2st64_b32 v206, v3, v2 offset0:28 offset1:29
	v_mul_f32_e32 v2, v0, v12
	v_mul_f32_e32 v4, v0, v13
	v_mul_f32_e32 v3, v0, v28
	ds_write2st64_b32 v206, v2, v4 offset0:14 offset1:15
	v_mul_f32_e32 v2, v0, v29
	ds_write2st64_b32 v206, v3, v2 offset0:30 offset1:31
	v_mul_f32_e32 v2, v0, v14
	v_mul_f32_e32 v4, v0, v15
	v_mul_f32_e32 v3, v0, v30
	ds_write2st64_b32 v206, v2, v4 offset0:16 offset1:17
	v_mul_f32_e32 v2, v0, v31
	ds_bpermute_b32 v20, v205, v123
	ds_write2st64_b32 v206, v3, v2 offset0:32 offset1:33
	v_mul_f32_e32 v2, v0, v16
	v_mul_f32_e32 v3, v0, v32
	v_mul_f32_e32 v4, v0, v17
	v_mul_f32_e32 v0, v0, v33
	ds_write2st64_b32 v206, v3, v0 offset0:34 offset1:35
	v_xor_b32_e32 v3, 1, v235
	v_cmp_lt_i32_e32 vcc, v3, v131
	ds_write2st64_b32 v206, v2, v4 offset0:18 offset1:19
	v_add_f32_e32 v4, v122, v123
	v_cndmask_b32_e32 v3, v235, v3, vcc
	v_add_f32_e32 v6, v120, v121
	v_cmp_gt_u32_e32 vcc, 32, v188
	v_add_f32_e32 v4, v6, v4
	v_lshlrev_b32_e32 v3, 2, v3
	s_waitcnt lgkmcnt(3)
	v_cndmask_b32_e64 v6, v20, 0, vcc
	v_add_f32_e32 v4, v6, v4
	s_nop 1
	v_mov_b32_dpp v6, v4 quad_perm:[1,0,3,2] row_mask:0xf bank_mask:0xf
	v_xor_b32_e32 v7, 2, v235
	v_cmp_lt_i32_e64 s[0:1], v7, v131
	ds_bpermute_b32 v19, v205, v117
	ds_bpermute_b32 v18, v205, v115
	v_cndmask_b32_e64 v7, v235, v7, s[0:1]
	v_lshlrev_b32_e32 v7, 2, v7
	s_waitcnt lgkmcnt(2)
	v_add_f32_e32 v21, v4, v6
	ds_bpermute_b32 v17, v205, v105
	ds_bpermute_b32 v16, v205, v61
	ds_bpermute_b32 v15, v205, v63
	ds_bpermute_b32 v14, v205, v99
	ds_bpermute_b32 v13, v205, v49
	ds_bpermute_b32 v12, v205, v55
	ds_bpermute_b32 v11, v205, v57
	ds_bpermute_b32 v10, v205, v97
	ds_bpermute_b32 v9, v205, v47
	ds_bpermute_b32 v8, v205, v73
	ds_bpermute_b32 v5, v205, v75
	ds_bpermute_b32 v0, v205, v71
	ds_bpermute_b32 v2, v205, v69
	s_nop 1
	v_mov_b32_dpp v22, v21 quad_perm:[2,3,0,1] row_mask:0xf bank_mask:0xf
	v_lshlrev_b32_e32 v4, 5, v129
	v_add_u32_e32 v6, v4, v196
	v_lshl_add_u32 v6, v6, 2, s83
	s_and_saveexec_b64 s[0:1], s[8:9]
	s_cbranch_execz .LBB0_1568
	s_waitcnt lgkmcnt(0)
	v_add_f32_e32 v21, v21, v22
	ds_write_b32 v6, v21

.LBB0_1623:
	s_waitcnt vmcnt(7)
	v_mov_b32_e32 v2, v0
	s_nop 1
	v_permlane32_swap_b32 v2, v0
	s_lshl_b64 s[8:9], s[18:19], 1
	s_waitcnt lgkmcnt(0)
	v_add_f32_e32 v0, v0, v2
	v_max_f32_e32 v0, 0xda24260, v0
	s_waitcnt vmcnt(0)
	v_div_scale_f32 v3, s[0:1], v0, v0, v234
	v_rcp_f32_e32 v4, v3
	v_readlane_b32 s0, v255, 24
	s_add_u32 s4, s0, s8
	v_readlane_b32 s0, v255, 25
	v_fma_f32 v5, -v3, v4, 1.0
	v_fmac_f32_e32 v4, v5, v4
	v_div_scale_f32 v5, vcc, v234, v0, v234
	v_mul_f32_e32 v6, v5, v4
	v_fma_f32 v7, -v3, v6, v5
	v_fmac_f32_e32 v6, v7, v4
	v_fma_f32 v3, -v3, v6, v5
	v_div_fmas_f32 v3, v3, v4, v6
	v_div_fixup_f32 v0, v3, v0, v234
	global_load_dword v234, v[150:151], off offset:8
	ds_read2st64_b32 v[2:3], v206 offset0:4 offset1:5
	ds_read2st64_b32 v[4:5], v206 offset0:20 offset1:21
	s_addc_u32 s5, s0, s9
	s_max_i32 s0, s89, 0x1ff
	s_addk_i32 s0, 0xfe01
	s_waitcnt lgkmcnt(1)
	v_fma_f32 v2, v16, v0, v2
	s_waitcnt lgkmcnt(0)
	v_fma_f32 v4, v32, v0, v4
	v_fmac_f32_e32 v3, v17, v0
	v_fmac_f32_e32 v5, v33, v0
	ds_write2st64_b32 v206, v2, v3 offset0:4 offset1:5
	ds_write2st64_b32 v206, v4, v5 offset0:20 offset1:21
	ds_read2st64_b32 v[2:3], v206 offset0:6 offset1:7
	ds_read2st64_b32 v[4:5], v206 offset0:22 offset1:23
	s_lshr_b32 s0, s0, 6
	s_cmp_gt_u32 s0, s48
	s_waitcnt lgkmcnt(1)
	v_fma_f32 v2, v18, v0, v2
	s_waitcnt lgkmcnt(0)
	v_fma_f32 v4, v34, v0, v4
	v_fmac_f32_e32 v3, v19, v0
	v_fmac_f32_e32 v5, v35, v0
	ds_write2st64_b32 v206, v2, v3 offset0:6 offset1:7
	ds_write2st64_b32 v206, v4, v5 offset0:22 offset1:23
	ds_read2st64_b32 v[2:3], v206 offset0:8 offset1:9
	ds_read2st64_b32 v[4:5], v206 offset0:24 offset1:25
	s_waitcnt lgkmcnt(1)
	v_fma_f32 v2, v20, v0, v2
	s_waitcnt lgkmcnt(0)
	v_fma_f32 v4, v36, v0, v4
	v_fmac_f32_e32 v3, v21, v0
	v_fmac_f32_e32 v5, v37, v0
	ds_write2st64_b32 v206, v2, v3 offset0:8 offset1:9
	ds_write2st64_b32 v206, v4, v5 offset0:24 offset1:25
	ds_read2st64_b32 v[2:3], v206 offset0:10 offset1:11
	ds_read2st64_b32 v[4:5], v206 offset0:26 offset1:27
	s_waitcnt lgkmcnt(1)
	v_fma_f32 v2, v22, v0, v2
	s_waitcnt lgkmcnt(0)
	v_fma_f32 v4, v38, v0, v4
	v_fmac_f32_e32 v3, v23, v0
	v_fmac_f32_e32 v5, v39, v0
	ds_write2st64_b32 v206, v2, v3 offset0:10 offset1:11
	ds_write2st64_b32 v206, v4, v5 offset0:26 offset1:27
	ds_read2st64_b32 v[2:3], v206 offset0:12 offset1:13
	ds_read2st64_b32 v[4:5], v206 offset0:28 offset1:29
	s_waitcnt lgkmcnt(1)
	v_fma_f32 v2, v24, v0, v2
	s_waitcnt lgkmcnt(0)
	v_fma_f32 v4, v40, v0, v4
	v_fmac_f32_e32 v3, v25, v0
	v_fmac_f32_e32 v5, v41, v0
	ds_write2st64_b32 v206, v2, v3 offset0:12 offset1:13
	ds_write2st64_b32 v206, v4, v5 offset0:28 offset1:29
	ds_read2st64_b32 v[2:3], v206 offset0:14 offset1:15
	ds_read2st64_b32 v[4:5], v206 offset0:30 offset1:31
	s_waitcnt lgkmcnt(1)
	v_fma_f32 v2, v26, v0, v2
	s_waitcnt lgkmcnt(0)
	v_fma_f32 v4, v42, v0, v4
	v_fmac_f32_e32 v3, v27, v0
	v_fmac_f32_e32 v5, v43, v0
	ds_write2st64_b32 v206, v2, v3 offset0:14 offset1:15
	ds_write2st64_b32 v206, v4, v5 offset0:30 offset1:31
	ds_read2st64_b32 v[2:3], v206 offset0:16 offset1:17
	ds_read2st64_b32 v[4:5], v206 offset0:32 offset1:33
	s_waitcnt lgkmcnt(1)
	v_fma_f32 v2, v28, v0, v2
	s_waitcnt lgkmcnt(0)
	v_fma_f32 v4, v44, v0, v4
	v_fmac_f32_e32 v3, v29, v0
	v_fmac_f32_e32 v5, v45, v0
	ds_write2st64_b32 v206, v2, v3 offset0:16 offset1:17
	ds_write2st64_b32 v206, v4, v5 offset0:32 offset1:33
	ds_read2st64_b32 v[2:3], v206 offset0:18 offset1:19
	ds_read2st64_b32 v[4:5], v206 offset0:34 offset1:35
	s_waitcnt lgkmcnt(1)
	v_fma_f32 v2, v30, v0, v2
	s_waitcnt lgkmcnt(0)
	v_fma_f32 v4, v46, v0, v4
	v_fmac_f32_e32 v3, v31, v0
	v_fmac_f32_e32 v5, v47, v0
	ds_write2st64_b32 v206, v2, v3 offset0:18 offset1:19
	ds_write2st64_b32 v206, v4, v5 offset0:34 offset1:35
	s_waitcnt lgkmcnt(0)
	s_cbranch_scc0 .LBB0_1626
	s_cmp_gt_i32 s0, s48
	s_cbranch_scc1 .LBB0_1490
	s_branch .LBB0_1631
